# NSA: permuted V tiles read with ds_read_b128, batched LDS reads in selected FAST path, true distance-2 tile prefetch, in-place PV accumulate, pipelined ballot top-k search with early exit, dropped one
# speedup vs baseline: 1.0395x; 1.0304x over previous
.LBB0_814:
	s_or_b64 exec, exec, s[0:1]
	s_mov_b32 s4, 30
	s_mov_b32 s41, 0
	s_mov_b32 s40, 0
	s_mov_b32 s38, 0
	s_mov_b32 s2, 0
	s_mov_b32 s74, 0
	s_mov_b32 s85, 0
	s_mov_b32 s88, 0
	s_mov_b32 s98, 0
.LBB0_815:
	s_lshl_b32 s5, 1, s4
	s_or_b32 s6, s5, s41
	s_or_b32 s8, s5, s40
	s_or_b32 s9, s5, s38
	s_or_b32 s12, s5, s2
	v_cmp_le_u32_e64 s[52:53], s6, v42
	v_cmp_le_u32_e64 s[54:55], s6, v40
	v_cmp_le_u32_e64 s[56:57], s6, v41
	v_cmp_le_u32_e64 s[58:59], s6, v35
	v_cmp_le_u32_e64 s[60:61], s8, v39
	v_cmp_le_u32_e64 s[62:63], s8, v37
	v_cmp_le_u32_e64 s[64:65], s8, v38
	v_cmp_le_u32_e64 s[66:67], s8, v36
	v_cmp_le_u32_e64 s[14:15], s9, v34
	v_cmp_le_u32_e64 s[16:17], s9, v32
	v_cmp_le_u32_e64 s[20:21], s9, v33
	v_cmp_le_u32_e64 s[0:1], s9, v31
	s_bcnt1_i32_b64 s7, s[52:53]
	s_bcnt1_i32_b64 s13, s[54:55]
	s_add_i32 s7, s7, s13
	s_bcnt1_i32_b64 s13, s[56:57]
	s_add_i32 s7, s7, s13
	s_bcnt1_i32_b64 s13, s[58:59]
	s_add_i32 s7, s7, s13
	v_cmp_le_u32_e64 s[52:53], s12, v30
	v_cmp_le_u32_e64 s[54:55], s12, v28
	v_cmp_le_u32_e64 s[56:57], s12, v29
	v_cmp_le_u32_e64 s[58:59], s12, v3
	s_cmp_gt_u32 s7, 12
	s_cselect_b32 s41, s6, s41
	s_cmp_eq_u32 s7, 13
	s_cselect_b32 s74, 1, s74
	s_bcnt1_i32_b64 s7, s[60:61]
	s_bcnt1_i32_b64 s13, s[62:63]
	s_add_i32 s7, s7, s13
	s_bcnt1_i32_b64 s13, s[64:65]
	s_add_i32 s7, s7, s13
	s_bcnt1_i32_b64 s13, s[66:67]
	s_add_i32 s7, s7, s13
	s_cmp_gt_u32 s7, 12
	s_cselect_b32 s40, s8, s40
	s_cmp_eq_u32 s7, 13
	s_cselect_b32 s85, 1, s85
	s_bcnt1_i32_b64 s7, s[14:15]
	s_bcnt1_i32_b64 s13, s[16:17]
	s_add_i32 s7, s7, s13
	s_bcnt1_i32_b64 s13, s[20:21]
	s_add_i32 s7, s7, s13
	s_bcnt1_i32_b64 s13, s[0:1]
	s_add_i32 s7, s7, s13
	s_cmp_gt_u32 s7, 12
	s_cselect_b32 s38, s9, s38
	s_cmp_eq_u32 s7, 13
	s_cselect_b32 s88, 1, s88
	s_bcnt1_i32_b64 s7, s[52:53]
	s_bcnt1_i32_b64 s13, s[54:55]
	s_add_i32 s7, s7, s13
	s_bcnt1_i32_b64 s13, s[56:57]
	s_add_i32 s7, s7, s13
	s_bcnt1_i32_b64 s13, s[58:59]
	s_add_i32 s7, s7, s13
	s_cmp_gt_u32 s7, 12
	s_cselect_b32 s2, s12, s2
	s_cmp_eq_u32 s7, 13
	s_cselect_b32 s98, 1, s98
	s_and_b32 s13, s74, s85
	s_and_b32 s13, s13, s88
	s_and_b32 s13, s13, s98
	s_cmp_lg_u32 s13, 0
	s_cbranch_scc1 .Lsel_done
	s_add_i32 s4, s4, -1
	s_cmp_lg_u32 s4, -1
	s_cbranch_scc1 .LBB0_815
.Lsel_done:
	v_cmp_lt_u32_e64 s[0:1], s41, v42
	s_bcnt1_i32_b64 s4, s[0:1]
	v_cmp_lt_u32_e64 s[0:1], s41, v40
	s_bcnt1_i32_b64 s5, s[0:1]
	v_cmp_lt_u32_e64 s[0:1], s41, v41
	s_bcnt1_i32_b64 s6, s[0:1]
	v_cmp_lt_u32_e64 s[0:1], s41, v35
	s_bcnt1_i32_b64 s0, s[0:1]
	s_add_i32 s1, s4, s5
	s_add_i32 s1, s1, s6
	s_add_i32 s1, s1, s0
	v_cmp_ge_u32_e64 s[8:9], s41, v42
	v_cmp_ge_u32_e64 s[12:13], s41, v40
	v_cmp_ge_u32_e64 s[14:15], s41, v41
	v_cmp_ge_u32_e64 s[16:17], s41, v35
	s_sub_i32 s74, 13, s1
	v_cmp_eq_u32_e64 s[0:1], s41, v42
	s_mov_b64 s[4:5], -1
	s_mov_b64 s[20:21], -1
	s_and_saveexec_b64 s[6:7], s[8:9]
	v_mbcnt_lo_u32_b32 v42, s0, 0
	v_mbcnt_hi_u32_b32 v42, s1, v42
	v_cmp_gt_i32_e64 s[8:9], s74, v42
	s_and_b64 s[8:9], s[0:1], s[8:9]
	s_orn2_b64 s[20:21], s[8:9], exec
	s_or_b64 exec, exec, s[6:7]
	s_bcnt1_i32_b64 s0, s[0:1]
	v_cndmask_b32_e64 v42, 0, 1, s[20:21]
	s_min_i32 s0, s74, s0
	v_cmp_ne_u32_e64 s[8:9], 0, v42
	s_sub_i32 s20, s74, s0
	v_cmp_eq_u32_e64 s[0:1], s41, v40
	s_and_saveexec_b64 s[6:7], s[12:13]
	s_nop 0
	v_mbcnt_lo_u32_b32 v40, s0, 0
	v_mbcnt_hi_u32_b32 v40, s1, v40
	v_cmp_gt_i32_e64 s[12:13], s20, v40
	s_and_b64 s[4:5], s[0:1], s[12:13]
	s_orn2_b64 s[4:5], s[4:5], exec
	s_or_b64 exec, exec, s[6:7]
	s_bcnt1_i32_b64 s0, s[0:1]
	v_cndmask_b32_e64 v40, 0, 1, s[4:5]
	s_min_i32 s0, s20, s0
	v_cmp_ne_u32_e64 s[12:13], 0, v40
	s_sub_i32 s74, s20, s0
	v_cmp_eq_u32_e64 s[0:1], s41, v41
	s_mov_b64 s[4:5], -1
	s_mov_b64 s[20:21], -1
	s_and_saveexec_b64 s[6:7], s[14:15]
	v_mbcnt_lo_u32_b32 v40, s0, 0
	v_mbcnt_hi_u32_b32 v40, s1, v40
	v_cmp_gt_i32_e64 s[14:15], s74, v40
	s_and_b64 s[14:15], s[0:1], s[14:15]
	s_orn2_b64 s[20:21], s[14:15], exec
	s_or_b64 exec, exec, s[6:7]
	v_cndmask_b32_e64 v40, 0, 1, s[20:21]
	v_cmp_ne_u32_e64 s[14:15], 0, v40
	v_cmp_eq_u32_e64 s[20:21], s41, v35
	s_and_saveexec_b64 s[6:7], s[16:17]
	s_bcnt1_i32_b64 s0, s[0:1]
	s_min_i32 s0, s74, s0
	v_mbcnt_lo_u32_b32 v35, s20, 0
	s_sub_i32 s0, s74, s0
	v_mbcnt_hi_u32_b32 v35, s21, v35
	v_cmp_gt_i32_e64 s[0:1], s0, v35
	s_and_b64 s[0:1], s[20:21], s[0:1]
	s_orn2_b64 s[4:5], s[0:1], exec
	s_or_b64 exec, exec, s[6:7]
	v_cndmask_b32_e64 v35, 0, 1, s[4:5]
	v_cmp_ne_u32_e64 s[16:17], 0, v35
	v_mov_b32_e32 v40, s8
	s_and_saveexec_b64 s[0:1], vcc
	s_xor_b64 s[4:5], exec, s[0:1]
	s_cbranch_execz .LBB0_846
	v_cmp_lt_i32_e64 s[0:1], 3, v86
	s_and_saveexec_b64 s[6:7], s[0:1]
	s_xor_b64 s[6:7], exec, s[6:7]
	s_cbranch_execz .LBB0_837
	v_cmp_lt_i32_e64 s[0:1], 5, v86
	s_and_saveexec_b64 s[20:21], s[0:1]
	s_xor_b64 s[20:21], exec, s[20:21]
	s_cbranch_execz .LBB0_832
	v_cmp_lt_i32_e64 s[0:1], 6, v86
	v_mov_b32_e32 v40, s16
	s_and_saveexec_b64 s[74:75], s[0:1]
	s_xor_b64 s[74:75], exec, s[74:75]
	s_cbranch_execz .LBB0_831
	v_cmp_eq_u32_e64 s[0:1], 7, v86
	v_mov_b32_e32 v40, 0
	s_and_saveexec_b64 s[78:79], s[0:1]
	v_mov_b32_e32 v40, s17
	s_or_b64 exec, exec, s[78:79]

.LBB0_970:
	s_add_i32 s15, s16, 2
	s_cmp_lt_i32 s15, s11
	s_cselect_b64 s[6:7], -1, 0
	s_cmp_ge_i32 s15, s11
	s_cselect_b64 s[0:1], -1, 0
	s_and_b64 vcc, exec, s[0:1]
	s_cbranch_vccnz .LBB0_972
	v_mov_b32_e32 v44, s14
	ds_read_b32 v46, v44 offset:4
	s_mov_b32 s2, 0x7c000
	s_waitcnt lgkmcnt(0)
	v_lshlrev_b32_e32 v48, 6, v46
	v_ashrrev_i32_e32 v49, 31, v48
	v_mad_i64_i32 v[44:45], s[4:5], v46, s2, v[84:85]
	v_lshl_add_u64 v[48:49], v[48:49], 1, v[86:87]
	global_load_dwordx4 v[44:47], v[44:45], off
	s_nop 0
	global_load_dwordx4 v[48:51], v[48:49], off

.LBB0_977:
	s_and_b64 vcc, exec, s[4:5]
	s_cbranch_vccz .LBB0_981
	s_nop 5
	ds_read_b128 v[160:163], v118
	ds_read_b128 v[164:167], v118 offset:64
	ds_read_b128 v[168:171], v118 offset:2304
	ds_read_b128 v[172:175], v118 offset:2368
	ds_read_b128 v[176:179], v118 offset:4608
	ds_read_b128 v[180:183], v118 offset:4672
	ds_read_b128 v[184:187], v118 offset:6912
	ds_read_b128 v[188:191], v118 offset:6976
	v_or_b32_e32 v60, v98, v108
	v_sub_u32_e32 v60, v103, v60
	v_cvt_f32_i32_e32 v60, v60
	s_mov_b32 s4, 2.0
	s_mov_b32 s5, 0x40400000
	v_mul_f32_e64 v60, -v96, v60
	v_cndmask_b32_e64 v68, v249, v60, s[8:9]
	v_pk_fma_f32 v[62:63], v[96:97], s[4:5], v[68:69] op_sel_hi:[1,1,0]
	s_mov_b32 s4, 0x41800000
	s_mov_b32 s5, 0x41880000
	v_fma_f32 v60, 0, v96, v68
	v_add_f32_e32 v61, v96, v68
	v_pk_fma_f32 v[66:67], v[90:91], s[90:91], v[68:69] op_sel_hi:[1,1,0]
	v_pk_fma_f32 v[64:65], v[88:89], s[4:5], v[68:69] op_sel_hi:[1,1,0]
	v_pk_fma_f32 v[78:79], v[90:91], s[92:93], v[68:69] op_sel_hi:[1,1,0]
	v_pk_fma_f32 v[76:77], v[88:89], s[34:35], v[68:69] op_sel_hi:[1,1,0]
	v_pk_fma_f32 v[110:111], v[90:91], s[22:23], v[68:69] op_sel_hi:[1,1,0]
	v_pk_fma_f32 v[108:109], v[88:89], s[72:73], v[68:69] op_sel_hi:[1,1,0]
	s_waitcnt lgkmcnt(7)
	v_mfma_f32_16x16x32_bf16 v[60:63], v[160:163], v[4:7], v[60:63]
	s_waitcnt lgkmcnt(6)
	v_mfma_f32_16x16x32_bf16 v[72:75], v[164:167], v[8:11], v[60:63]
	ds_read_b128 v[196:199], v243
	ds_read_b128 v[200:203], v243 offset:64
	s_waitcnt lgkmcnt(7)
	v_mfma_f32_16x16x32_bf16 v[60:63], v[168:171], v[4:7], v[64:67]
	s_waitcnt lgkmcnt(6)
	v_mfma_f32_16x16x32_bf16 v[68:71], v[172:175], v[8:11], v[60:63]
	ds_read_b128 v[204:207], v243 offset:2304
	ds_read_b128 v[208:211], v243 offset:2368
	s_waitcnt lgkmcnt(7)
	v_mfma_f32_16x16x32_bf16 v[60:63], v[176:179], v[4:7], v[76:79]
	s_waitcnt lgkmcnt(6)
	v_mfma_f32_16x16x32_bf16 v[60:63], v[180:183], v[8:11], v[60:63]
	ds_read_b128 v[212:215], v243 offset:4608
	ds_read_b128 v[216:219], v243 offset:4672
	s_waitcnt lgkmcnt(7)
	v_mfma_f32_16x16x32_bf16 v[64:67], v[184:187], v[4:7], v[108:111]
	s_waitcnt lgkmcnt(6)
	v_mfma_f32_16x16x32_bf16 v[64:67], v[188:191], v[8:11], v[64:67]
	ds_read_b128 v[220:223], v243 offset:6912
	ds_read_b128 v[224:227], v243 offset:6976
	v_max3_f32 v76, v72, s36, v73
	v_max3_f32 v76, v76, v74, v75
	v_max3_f32 v76, v76, v68, v69
	v_max3_f32 v76, v76, v70, v71
	v_max3_f32 v76, v76, v60, v61
	v_max3_f32 v76, v76, v62, v63
	s_nop 1
	v_max3_f32 v76, v76, v64, v65
	v_max3_f32 v76, v76, v66, v67
	v_cmp_gt_f32_e32 vcc, v76, v106
	s_cbranch_vccz .LBB0_980
	ds_bpermute_b32 v77, v115, v76
	v_max_f32_e32 v76, v76, v76
	s_waitcnt lgkmcnt(0)
	v_max_f32_e32 v77, v77, v77
	v_max_f32_e32 v76, v76, v77
	ds_bpermute_b32 v77, v114, v76
	s_waitcnt lgkmcnt(0)
	v_max3_f32 v77, v106, v76, v77
	v_sub_f32_e32 v76, v106, v77
	v_exp_f32_e32 v76, v76
	v_mov_b32_e32 v106, v77
	v_mul_f32_e32 v107, v107, v76
	v_pk_mul_f32 v[42:43], v[42:43], v[76:77] op_sel_hi:[1,0]
	v_pk_mul_f32 v[40:41], v[40:41], v[76:77] op_sel_hi:[1,0]
	v_pk_mul_f32 v[38:39], v[38:39], v[76:77] op_sel_hi:[1,0]
	v_pk_mul_f32 v[36:37], v[36:37], v[76:77] op_sel_hi:[1,0]
	v_pk_mul_f32 v[34:35], v[34:35], v[76:77] op_sel_hi:[1,0]
	v_pk_mul_f32 v[32:33], v[32:33], v[76:77] op_sel_hi:[1,0]
	v_pk_mul_f32 v[30:31], v[30:31], v[76:77] op_sel_hi:[1,0]
	v_pk_mul_f32 v[28:29], v[28:29], v[76:77] op_sel_hi:[1,0]
.LBB0_980:
	v_sub_f32_e32 v72, v72, v106
	v_exp_f32_e32 v72, v72
	v_sub_f32_e32 v73, v73, v106
	v_exp_f32_e32 v73, v73
	v_sub_f32_e32 v74, v74, v106
	v_exp_f32_e32 v74, v74
	v_sub_f32_e32 v75, v75, v106
	v_exp_f32_e32 v75, v75
	v_sub_f32_e32 v68, v68, v106
	v_add_f32_e32 v76, 0, v72
	v_exp_f32_e32 v68, v68
	v_sub_f32_e32 v69, v69, v106
	v_add_f32_e32 v76, v73, v76
	v_exp_f32_e32 v69, v69
	v_sub_f32_e32 v70, v70, v106
	v_add_f32_e32 v76, v74, v76
	v_exp_f32_e32 v70, v70
	v_sub_f32_e32 v71, v71, v106
	v_add_f32_e32 v76, v75, v76
	v_exp_f32_e32 v71, v71
	v_sub_f32_e32 v60, v60, v106
	v_add_f32_e32 v76, v68, v76
	v_exp_f32_e32 v60, v60
	v_sub_f32_e32 v61, v61, v106
	v_add_f32_e32 v76, v69, v76
	v_exp_f32_e32 v61, v61
	v_sub_f32_e32 v62, v62, v106
	v_add_f32_e32 v76, v70, v76
	v_exp_f32_e32 v62, v62
	v_sub_f32_e32 v63, v63, v106
	v_add_f32_e32 v108, v71, v76
	v_exp_f32_e32 v63, v63
	v_sub_f32_e32 v64, v64, v106
	v_cvt_pk_bf16_f32 v78, v68, v69
	v_add_f32_e32 v68, v60, v108
	v_exp_f32_e32 v64, v64
	v_sub_f32_e32 v65, v65, v106
	v_add_f32_e32 v68, v61, v68
	v_exp_f32_e32 v65, v65
	v_sub_f32_e32 v66, v66, v106
	v_add_f32_e32 v68, v62, v68
	v_exp_f32_e32 v66, v66
	v_sub_f32_e32 v67, v67, v106
	v_add_f32_e32 v68, v63, v68
	v_exp_f32_e32 v67, v67
	v_add_f32_e32 v68, v64, v68
	v_add_f32_e32 v68, v65, v68
	v_add_f32_e32 v68, v66, v68
	v_add_f32_e32 v68, v67, v68
	v_cvt_pk_bf16_f32 v60, v60, v61
	v_cvt_pk_bf16_f32 v61, v62, v63
	v_cvt_pk_bf16_f32 v62, v64, v65
	v_cvt_pk_bf16_f32 v63, v66, v67
	v_cvt_pk_bf16_f32 v76, v72, v73
	v_cvt_pk_bf16_f32 v77, v74, v75
	v_cvt_pk_bf16_f32 v79, v70, v71
	v_add_f32_e32 v107, v107, v68
	s_waitcnt lgkmcnt(0)
	v_mfma_f32_16x16x32_bf16 v[40:43], v[196:199], v[76:79], v[40:43]
	v_mfma_f32_16x16x32_bf16 v[36:39], v[204:207], v[76:79], v[36:39]
	v_mfma_f32_16x16x32_bf16 v[32:35], v[212:215], v[76:79], v[32:35]
	v_mfma_f32_16x16x32_bf16 v[28:31], v[220:223], v[76:79], v[28:31]
	v_mfma_f32_16x16x32_bf16 v[40:43], v[200:203], v[60:63], v[40:43]
	v_mfma_f32_16x16x32_bf16 v[36:39], v[208:211], v[60:63], v[36:39]
	v_mfma_f32_16x16x32_bf16 v[32:35], v[216:219], v[60:63], v[32:35]
	v_mfma_f32_16x16x32_bf16 v[28:31], v[224:227], v[60:63], v[28:31]
	s_branch .LBB0_982

.LBB0_982:
	s_add_i32 s2, s16, 1
	s_cmp_lt_i32 s2, s11
	s_cselect_b64 s[4:5], -1, 0
	s_cmp_ge_i32 s2, s11
	s_cbranch_scc1 .LBB0_984
	s_and_b64 vcc, exec, s[6:7]
	s_cbranch_vccz .Lsel_e_old
	s_waitcnt vmcnt(3)
	ds_write_b128 v113, v[52:55]
	s_waitcnt vmcnt(2)
	ds_write2_b64 v242, v[56:57], v[58:59] offset1:2
	s_branch .LBB0_984

.LBB0_984:
	s_andn2_b64 vcc, exec, s[4:5]
	s_mov_b64 s[4:5], -1
	s_waitcnt lgkmcnt(0)
	s_barrier
	s_cbranch_vccnz .LBB0_968
	s_add_i32 s2, s16, 3
	s_cmp_ge_i32 s2, s11
	s_cbranch_scc1 .LBB0_987
	v_mov_b32_e32 v52, s14
	ds_read_b32 v54, v52
	s_mov_b32 s2, 0x7c000
	s_waitcnt lgkmcnt(0)
	v_lshlrev_b32_e32 v56, 6, v54
	v_ashrrev_i32_e32 v57, 31, v56
	v_mad_i64_i32 v[52:53], s[4:5], v54, s2, v[84:85]
	v_lshl_add_u64 v[56:57], v[56:57], 1, v[86:87]
	global_load_dwordx4 v[52:55], v[52:53], off
	s_nop 0
	global_load_dwordx4 v[56:59], v[56:57], off

.LBB0_992:
	s_and_b64 vcc, exec, s[4:5]
	s_cbranch_vccz .LBB0_996
	s_nop 5
	ds_read_b128 v[160:163], v119
	ds_read_b128 v[164:167], v119 offset:64
	ds_read_b128 v[168:171], v119 offset:2304
	ds_read_b128 v[172:175], v119 offset:2368
	ds_read_b128 v[176:179], v119 offset:4608
	ds_read_b128 v[180:183], v119 offset:4672
	ds_read_b128 v[184:187], v119 offset:6912
	ds_read_b128 v[188:191], v119 offset:6976
	v_or_b32_e32 v60, v98, v108
	v_sub_u32_e32 v60, v103, v60
	v_cvt_f32_i32_e32 v60, v60
	s_mov_b32 s4, 2.0
	s_mov_b32 s5, 0x40400000
	v_mul_f32_e64 v60, -v96, v60
	v_cndmask_b32_e64 v68, v249, v60, s[8:9]
	v_pk_fma_f32 v[62:63], v[96:97], s[4:5], v[68:69] op_sel_hi:[1,1,0]
	s_mov_b32 s4, 0x41800000
	s_mov_b32 s5, 0x41880000
	v_fma_f32 v60, 0, v96, v68
	v_add_f32_e32 v61, v96, v68
	v_pk_fma_f32 v[66:67], v[90:91], s[90:91], v[68:69] op_sel_hi:[1,1,0]
	v_pk_fma_f32 v[64:65], v[88:89], s[4:5], v[68:69] op_sel_hi:[1,1,0]
	v_pk_fma_f32 v[78:79], v[90:91], s[92:93], v[68:69] op_sel_hi:[1,1,0]
	v_pk_fma_f32 v[76:77], v[88:89], s[34:35], v[68:69] op_sel_hi:[1,1,0]
	v_pk_fma_f32 v[110:111], v[90:91], s[22:23], v[68:69] op_sel_hi:[1,1,0]
	v_pk_fma_f32 v[108:109], v[88:89], s[72:73], v[68:69] op_sel_hi:[1,1,0]
	s_waitcnt lgkmcnt(7)
	v_mfma_f32_16x16x32_bf16 v[60:63], v[160:163], v[4:7], v[60:63]
	s_waitcnt lgkmcnt(6)
	v_mfma_f32_16x16x32_bf16 v[72:75], v[164:167], v[8:11], v[60:63]
	ds_read_b128 v[196:199], v244
	ds_read_b128 v[200:203], v244 offset:64
	s_waitcnt lgkmcnt(7)
	v_mfma_f32_16x16x32_bf16 v[60:63], v[168:171], v[4:7], v[64:67]
	s_waitcnt lgkmcnt(6)
	v_mfma_f32_16x16x32_bf16 v[68:71], v[172:175], v[8:11], v[60:63]
	ds_read_b128 v[204:207], v244 offset:2304
	ds_read_b128 v[208:211], v244 offset:2368
	s_waitcnt lgkmcnt(7)
	v_mfma_f32_16x16x32_bf16 v[60:63], v[176:179], v[4:7], v[76:79]
	s_waitcnt lgkmcnt(6)
	v_mfma_f32_16x16x32_bf16 v[60:63], v[180:183], v[8:11], v[60:63]
	ds_read_b128 v[212:215], v244 offset:4608
	ds_read_b128 v[216:219], v244 offset:4672
	s_waitcnt lgkmcnt(7)
	v_mfma_f32_16x16x32_bf16 v[64:67], v[184:187], v[4:7], v[108:111]
	s_waitcnt lgkmcnt(6)
	v_mfma_f32_16x16x32_bf16 v[64:67], v[188:191], v[8:11], v[64:67]
	ds_read_b128 v[220:223], v244 offset:6912
	ds_read_b128 v[224:227], v244 offset:6976
	v_max3_f32 v76, v72, s36, v73
	v_max3_f32 v76, v76, v74, v75
	v_max3_f32 v76, v76, v68, v69
	v_max3_f32 v76, v76, v70, v71
	v_max3_f32 v76, v76, v60, v61
	v_max3_f32 v76, v76, v62, v63
	s_nop 1
	v_max3_f32 v76, v76, v64, v65
	v_max3_f32 v76, v76, v66, v67
	v_cmp_gt_f32_e32 vcc, v76, v106
	s_cbranch_vccz .LBB0_995
	ds_bpermute_b32 v77, v115, v76
	v_max_f32_e32 v76, v76, v76
	s_waitcnt lgkmcnt(0)
	v_max_f32_e32 v77, v77, v77
	v_max_f32_e32 v76, v76, v77
	ds_bpermute_b32 v77, v114, v76
	s_waitcnt lgkmcnt(0)
	v_max3_f32 v77, v106, v76, v77
	v_sub_f32_e32 v76, v106, v77
	v_exp_f32_e32 v76, v76
	v_mov_b32_e32 v106, v77
	v_mul_f32_e32 v107, v107, v76
	v_pk_mul_f32 v[42:43], v[42:43], v[76:77] op_sel_hi:[1,0]
	v_pk_mul_f32 v[40:41], v[40:41], v[76:77] op_sel_hi:[1,0]
	v_pk_mul_f32 v[38:39], v[38:39], v[76:77] op_sel_hi:[1,0]
	v_pk_mul_f32 v[36:37], v[36:37], v[76:77] op_sel_hi:[1,0]
	v_pk_mul_f32 v[34:35], v[34:35], v[76:77] op_sel_hi:[1,0]
	v_pk_mul_f32 v[32:33], v[32:33], v[76:77] op_sel_hi:[1,0]
	v_pk_mul_f32 v[30:31], v[30:31], v[76:77] op_sel_hi:[1,0]
	v_pk_mul_f32 v[28:29], v[28:29], v[76:77] op_sel_hi:[1,0]

.LBB0_997:
	s_andn2_b64 vcc, exec, s[6:7]
	s_cbranch_vccnz .LBB0_999
	s_add_i32 s2, s16, 3
	s_cmp_lt_i32 s2, s11
	s_cbranch_scc0 .Lsel_o_old
	s_waitcnt vmcnt(3)
	ds_write_b128 v112, v[44:47]
	s_waitcnt vmcnt(2)
	ds_write2_b64 v238, v[48:49], v[50:51] offset1:2
	s_branch .LBB0_999
.Lsel_o_old:
	s_waitcnt vmcnt(1)
	ds_write_b128 v112, v[44:47]
	s_waitcnt vmcnt(0)
	ds_write2_b64 v238, v[48:49], v[50:51] offset1:2
.LBB0_999:
	s_waitcnt lgkmcnt(0)
	s_barrier
	s_add_i32 s14, s14, -8
	s_mov_b64 s[4:5], s[0:1]
	s_and_b64 vcc, exec, s[4:5]
	s_cbranch_vccz .LBB0_969
	s_branch .LBB0_1001

.LBB0_1758:
	s_mov_b64 s[0:1], -1
	s_branch .LBB0_1807
	s_waitcnt vmcnt(0)
	s_barrier
	s_and_saveexec_b64 s[0:1], s[86:87]
	s_cbranch_execz .LBB0_1806
	v_mov_b32_e32 v0, 0x24000
	s_waitcnt vmcnt(0) expcnt(0) lgkmcnt(0)
	ds_read_b32 v3, v0
	v_mov_b32_e32 v0, 0x24004
	ds_read_b32 v2, v0
	s_waitcnt lgkmcnt(1)
	v_cmp_ne_u32_e32 vcc, 0, v3
	s_cbranch_vccnz .LBB0_1774
	s_mov_b32 s2, 1
	s_branch .LBB0_1762
